# grid barrier release flattened: every workgroup polls the monotonic cross-XCD arrival counter (drops TOPGEN/XGEN hops)
# speedup vs baseline: 1.0572x; 1.0045x over previous
.LBB0_7:
	s_cmp_ge_i32 s68, s69
	s_cbranch_scc1 .LBB0_634
	s_cmp_eq_u32 s70, 2
	s_cselect_b64 s[4:5], -1, 0
	s_waitcnt lgkmcnt(0)
	s_add_u32 s54, s74, 0x200
	s_addc_u32 s55, s75, 0
	s_add_u32 s56, s74, 0x1000
	s_addc_u32 s57, s75, 0
	v_writelane_b32 v254, s4, 2
	v_lshrrev_b32_e32 v1, 20, v0
	v_lshrrev_b32_e32 v0, 10, v0
	s_add_u32 s58, s74, 0x1100
	v_writelane_b32 v254, s5, 3
	v_or_b32_e32 v0, v0, v1
	s_movk_i32 s4, 0x3ff
	s_addc_u32 s59, s75, 0
	v_and_or_b32 v0, v0, s4, v137
	s_load_dword s4, s[0:1], 0xc8
	s_add_u32 s22, s74, 0x1200
	s_addc_u32 s23, s75, 0
	s_add_u32 s86, s74, 0x1300
	s_addc_u32 s87, s75, 0
	s_mul_i32 s3, s47, s46
	s_cmp_eq_u32 s8, 15
	s_waitcnt lgkmcnt(0)
	s_mul_i32 s45, s3, s4
	s_cselect_b64 s[4:5], -1, 0
	v_writelane_b32 v254, s4, 4
	s_cmp_eq_u32 s8, 14
	s_mov_b32 s12, s46
	v_writelane_b32 v254, s5, 5
	s_cselect_b64 s[4:5], -1, 0
	v_writelane_b32 v254, s4, 6
	s_cmp_eq_u32 s8, 13
	s_movk_i32 s99, 0x100
	v_writelane_b32 v254, s5, 7
	s_cselect_b64 s[4:5], -1, 0
	v_writelane_b32 v254, s4, 8
	s_cmp_eq_u32 s8, 12
	v_writelane_b32 v255, s56, 0
	v_writelane_b32 v254, s5, 9
	s_cselect_b64 s[4:5], -1, 0
	v_writelane_b32 v254, s4, 10
	s_cmp_eq_u32 s8, 11
	v_writelane_b32 v255, s57, 1
	v_writelane_b32 v254, s5, 11
	s_cselect_b64 s[4:5], -1, 0
	v_writelane_b32 v254, s4, 12
	s_cmp_eq_u32 s8, 10
	v_writelane_b32 v255, s58, 2
	v_writelane_b32 v254, s5, 13
	s_cselect_b64 s[4:5], -1, 0
	v_writelane_b32 v254, s4, 14
	s_cmp_eq_u32 s8, 9
	v_writelane_b32 v255, s59, 3
	v_writelane_b32 v254, s5, 15
	s_cselect_b64 s[4:5], -1, 0
	v_writelane_b32 v254, s4, 16
	s_cmp_eq_u32 s8, 8
	v_writelane_b32 v255, s22, 4
	v_writelane_b32 v254, s5, 17
	s_cselect_b64 s[4:5], -1, 0
	v_writelane_b32 v254, s4, 18
	s_cmp_eq_u32 s8, 7
	v_mov_b32_e32 v163, 0
	v_writelane_b32 v254, s5, 19
	s_cselect_b64 s[4:5], -1, 0
	v_writelane_b32 v254, s4, 20
	s_cmp_eq_u32 s8, 6
	s_movk_i32 s76, 0x1600
	v_writelane_b32 v254, s5, 21
	s_cselect_b64 s[4:5], -1, 0
	v_writelane_b32 v254, s4, 22
	s_cmp_eq_u32 s8, 5
	v_mov_b32_e32 v208, 0x3ecc95a3
	v_writelane_b32 v254, s5, 23
	s_cselect_b64 s[4:5], -1, 0
	v_writelane_b32 v254, s4, 24
	s_cmp_eq_u32 s8, 4
	v_mov_b32_e32 v209, 0x358637bd
	v_writelane_b32 v254, s5, 25
	s_cselect_b64 s[4:5], -1, 0
	v_writelane_b32 v254, s4, 26
	s_cmp_eq_u32 s8, 3
	v_mov_b32_e32 v210, 0x260
	v_writelane_b32 v254, s5, 27
	s_cselect_b64 s[4:5], -1, 0
	v_writelane_b32 v254, s4, 28
	s_cmp_eq_u32 s8, 2
	v_mov_b32_e32 v211, 0x100000
	v_writelane_b32 v254, s5, 29
	s_cselect_b64 s[4:5], -1, 0
	v_writelane_b32 v254, s4, 30
	s_cmp_eq_u32 s8, 1
	v_mov_b32_e32 v212, 1
	v_writelane_b32 v254, s5, 31
	s_cselect_b64 s[4:5], -1, 0
	v_writelane_b32 v254, s4, 32
	s_cmp_eq_u32 s8, 0
	v_mov_b32_e32 v219, 0x80
	v_writelane_b32 v254, s5, 33
	s_cselect_b64 s[4:5], -1, 0
	s_lshl_b32 s3, s8, 8
	v_writelane_b32 v254, s4, 34
	s_add_u32 s3, s74, s3
	v_bfrev_b32_e32 v213, 0.5
	v_writelane_b32 v254, s5, 35
	s_addc_u32 s4, s75, 0
	s_add_u32 s6, s3, 0x1400
	s_addc_u32 s7, s4, 0
	v_writelane_b32 v254, s6, 36
	v_mov_b32_e32 v216, 5
	v_mov_b32_e32 v217, 0x900
	v_writelane_b32 v254, s7, 37
	s_add_u32 s6, s3, 0x2400
	s_addc_u32 s7, s4, 0
	v_writelane_b32 v254, s6, 38
	s_add_u32 s4, s74, 0x3400
	s_addc_u32 s5, s75, 0
	v_writelane_b32 v254, s7, 39
	v_writelane_b32 v254, s4, 40
	v_cmp_eq_u32_e64 s[6:7], 0, v0
	v_mov_b32_e32 v218, 6
	v_writelane_b32 v254, s5, 41
	s_add_u32 s4, s74, 0x3500
	s_addc_u32 s5, s75, 0
	v_writelane_b32 v254, s4, 42
	s_add_i32 s3, 0, 0x23000
	v_mov_b32_e32 v220, 0x7f800000
	v_writelane_b32 v254, s5, 43
	v_writelane_b32 v254, s3, 44
	s_add_i32 s3, 0, 0x23800
	v_writelane_b32 v254, s3, 45
	s_add_i32 s3, 0, 0x14040
	v_writelane_b32 v254, s3, 46
	s_add_i32 s3, 0, 0xdc00
	v_writelane_b32 v254, s3, 47
	s_add_i32 s3, 0, 0x257c0
	v_writelane_b32 v254, s3, 48
	s_add_i32 s3, 0, 0x257c4
	v_writelane_b32 v254, s3, 49
	v_writelane_b32 v254, s6, 50
	v_mov_b32_e32 v221, 0x1a00
	v_mov_b32_e32 v222, 0xa000
	v_writelane_b32 v254, s7, 51
	v_cmp_eq_u32_e64 s[6:7], 0, v137
	v_mov_b32_e32 v223, 0x2100
	v_mov_b32_e32 v224, 0x4200
	v_writelane_b32 v254, s6, 52
	v_mov_b32_e32 v225, 0x6300
	v_mov_b32_e32 v226, 2
	v_writelane_b32 v254, s7, 53
	v_writelane_b32 v254, s2, 54
	v_writelane_b32 v254, s0, 55
	v_mov_b32_e32 v227, 0xcf
	v_mov_b32_e32 v228, 0x3e38aa3b
	v_writelane_b32 v254, s1, 56
	v_writelane_b32 v254, s12, 57
	s_movk_i32 s77, 0x210
	s_mov_b32 s83, 0xb00000
	v_writelane_b32 v254, s13, 58
	v_writelane_b32 v254, s52, 59
	s_mov_b32 s10, 0xf149f2ca
	s_mov_b32 s11, 0xffff0000
	v_writelane_b32 v254, s53, 60
	v_writelane_b32 v254, s45, 61
	v_writelane_b32 v254, s54, 62
	s_mov_b32 s33, 0x3600000
	s_mov_b32 s48, 0xbfb8aa3b
	s_mov_b32 s82, 0xc2ce8ed0
	s_mov_b32 s49, 0x42b17218
	s_movk_i32 s78, 0xe000
	s_movk_i32 s79, 0x108
	s_movk_i32 s90, 0x90
	s_mov_b32 s91, 0x5040100
	s_mov_b32 s5, 0xf800000
	s_mov_b32 s97, 0
	s_mov_b32 s4, 0x3fb8aa3b
	s_mov_b64 s[6:7], 0x16000
	s_mov_b64 s[8:9], 0x80
	v_writelane_b32 v254, s55, 63
	v_writelane_b32 v255, s23, 5
	s_branch .LBB0_12
.LBB0_10:
	s_or_b64 exec, exec, s[12:13]
	s_waitcnt lgkmcnt(0)
	s_barrier

.LBB0_603:
	v_readlane_b32 s14, v254, 36
	v_readlane_b32 s15, v254, 37
	v_cvt_f32_u32_e32 v1, v2
	v_sub_u32_e32 v4, 0, v2
	v_rcp_iflag_f32_e32 v1, v1
	s_nop 1
	global_atomic_add v3, v163, v212, s[14:15] sc0
	v_mul_f32_e32 v1, 0x4f7ffffe, v1
	v_cvt_u32_f32_e32 v1, v1
	v_mul_lo_u32 v4, v4, v1
	v_mul_hi_u32 v4, v1, v4
	v_add_u32_e32 v1, v1, v4
	s_waitcnt vmcnt(0)
	v_mul_hi_u32 v1, v3, v1
	v_mul_lo_u32 v4, v1, v2
	v_sub_u32_e32 v4, v3, v4
	v_add_u32_e32 v5, 1, v1
	v_cmp_ge_u32_e32 vcc, v4, v2
	v_add_u32_e32 v3, 1, v3
	s_nop 0
	v_cndmask_b32_e32 v1, v1, v5, vcc
	v_sub_u32_e32 v5, v4, v2
	v_cndmask_b32_e32 v4, v4, v5, vcc
	v_add_u32_e32 v5, 1, v1
	v_cmp_ge_u32_e32 vcc, v4, v2
	s_nop 1
	v_cndmask_b32_e32 v1, v1, v5, vcc
	v_mul_lo_u32 v4, v2, v1
	v_add_u32_e32 v2, v4, v2
	v_cmp_ne_u32_e32 vcc, v3, v2
	v_readlane_b32 s16, v254, 40
	v_readlane_b32 s17, v254, 41
	s_waitcnt lgkmcnt(0)
	v_add_u32_e32 v4, 1, v1
	v_mul_lo_u32 v4, v4, v0
	s_mov_b64 s[14:15], exec
	s_andn2_b64 exec, exec, vcc
	s_nop 4
	s_cbranch_execz .Lmy_xb_poll
	buffer_wbl2 sc1
	s_waitcnt vmcnt(0)
	global_atomic_add v163, v212, s[16:17]
.Lmy_xb_poll:
	s_mov_b64 exec, s[14:15]
	s_mov_b32 s3, 0
.Lmy_xb_spin:
	global_load_dword v5, v163, s[16:17] sc1
	s_waitcnt vmcnt(0)
	v_cmp_ge_u32_e32 vcc, v5, v4
	s_cbranch_vccnz .Lmy_xb_done
	s_sleep 1
	s_add_i32 s3, s3, 1
	s_cmp_lt_u32 s3, 0x20000
	s_cbranch_scc1 .Lmy_xb_spin
.Lmy_xb_done:
	buffer_inv sc1
	s_waitcnt vmcnt(0)
	s_branch .LBB0_10
